# GDN scan loop: u/g prefetch into dedicated registers copied at the next step bottom, counted vmcnt before record ds_writes, post-barrier vmcnt(0) removed
# baseline (speedup 1.0000x reference)
; #define SC_LOAD(R, U, G, CK) do { const char* rn_ = recs + (size_t)(CK) * REC; \
;         _Pragma("unroll") for (int i_ = 0; i_ < 8; ++i_) R[i_] = *(const u32x4*)(rn_ + (tid + 256 * i_) * 16); \
;         _Pragma("unroll") for (int c_ = 0; c_ < 4; ++c_) U[c_] = *(const u32x2*)(rn_ + uoff + c_ * 32); G = glp[CK]; } while (0)
; #define SC_STORE(R, BUF) do { char* nb_ = smem + (BUF) * 36864; \
;         _Pragma("unroll") for (int i_ = 0; i_ < 8; ++i_) { const int cid_ = tid + 256 * i_, mat_ = cid_ >> 9, row_ = (cid_ >> 3) & 63, cc_ = cid_ & 7; \
;             *(u32x4*)(nb_ + mat_ * 9216 + row_ * 144 + cc_ * 16) = R[i_]; } } while (0)
; DI void gdn_scan_block(const Params& p, int bh, char* smem) {
;     ...
;     const int uoff = 32768 + ((e0 + fr) * 64 + fq * 4) * 2;
;     u32x4 r1[8]; u32x2 u1[4], uc[4]; float g1, gl;
;     ...
;     SC_LOAD(r1, u1, g1, 0);
;     SC_STORE(r1, 0);
; #pragma unroll
;     for (int c = 0; c < 4; ++c) uc[c] = u1[c];
;     gl = g1;
;     SC_LOAD(r1, u1, g1, 1);
;     __syncthreads();
;     f32x4 S[4];
; #pragma unroll
;     for (int i = 0; i < 4; ++i) S[i] = (f32x4){0.f, 0.f, 0.f, 0.f};
.LBB0_450:
	s_or_b64 exec, exec, s[4:5]
	v_readlane_b32 s4, v250, 7
	v_readlane_b32 s5, v250, 8
	s_andn2_b64 vcc, exec, s[4:5]
	s_waitcnt lgkmcnt(0)
	s_barrier
	s_cbranch_vccnz .LBB0_454
	v_mov_b32_e32 v33, v210
	v_readlane_b32 s10, v250, 11
	v_lshlrev_b32_e32 v100, 4, v33
	v_ashrrev_i32_e32 v101, 31, v100
	v_readlane_b32 s11, v250, 12
	v_add_u32_e32 v102, 0x1000, v100
	v_ashrrev_i32_e32 v103, 31, v102
	v_lshl_add_u64 v[0:1], s[10:11], 0, v[100:101]
	global_load_dwordx4 v[0:3], v[0:1], off
	v_lshl_add_u64 v[4:5], s[10:11], 0, v[102:103]
	global_load_dwordx4 v[4:7], v[4:5], off
	v_add_u32_e32 v104, 0x2000, v100
	v_ashrrev_i32_e32 v105, 31, v104
	v_lshl_add_u64 v[8:9], s[10:11], 0, v[104:105]
	global_load_dwordx4 v[8:11], v[8:9], off
	v_add_u32_e32 v106, 0x3000, v100
	v_ashrrev_i32_e32 v107, 31, v106
	v_lshl_add_u64 v[12:13], s[10:11], 0, v[106:107]
	global_load_dwordx4 v[12:15], v[12:13], off
	v_add_u32_e32 v108, 0x4000, v100
	v_ashrrev_i32_e32 v109, 31, v108
	v_lshl_add_u64 v[16:17], s[10:11], 0, v[108:109]
	global_load_dwordx4 v[16:19], v[16:17], off
	v_add_u32_e32 v110, 0x5000, v100
	v_ashrrev_i32_e32 v111, 31, v110
	v_lshl_add_u64 v[20:21], s[10:11], 0, v[110:111]
	global_load_dwordx4 v[20:23], v[20:21], off
	v_add_u32_e32 v112, 0x6000, v100
	v_ashrrev_i32_e32 v113, 31, v112
	v_lshl_add_u64 v[24:25], s[10:11], 0, v[112:113]
	global_load_dwordx4 v[24:27], v[24:25], off
	v_add_u32_e32 v114, 0x7000, v100
	v_ashrrev_i32_e32 v115, 31, v114
	v_lshl_add_u64 v[28:29], s[10:11], 0, v[114:115]
	global_load_dwordx4 v[28:31], v[28:29], off
	v_bfe_u32 v34, v33, 4, 2
	v_ashrrev_i32_e32 v36, 2, v33
	v_lshlrev_b32_e32 v37, 3, v34
	v_and_b32_e32 v32, -16, v36
	v_bfi_b32 v36, -16, v36, v33
	v_lshl_or_b32 v36, v36, 7, v37
	v_add_u32_e32 v116, 0x8000, v36
	v_ashrrev_i32_e32 v117, 31, v116
	v_lshl_add_u64 v[36:37], s[10:11], 0, v[116:117]
	global_load_dwordx2 v[54:55], v[36:37], off
	global_load_dwordx2 v[52:53], v[36:37], off offset:32
	global_load_dwordx2 v[50:51], v[36:37], off offset:64
	global_load_dwordx2 v[48:49], v[36:37], off offset:96
	v_ashrrev_i32_e32 v36, 9, v33
	v_bfe_u32 v37, v33, 3, 6
	s_movk_i32 s4, 0x2400
	v_and_b32_e32 v130, 0x70, v100
	v_mul_i32_i24_e32 v131, 0x2400, v36
	v_mad_i32_i24 v36, v36, s4, 0
	v_mul_u32_u24_e32 v132, 0x90, v37
	v_add3_u32 v36, v36, v132, v130
	v_readlane_b32 s12, v250, 9
	v_readlane_b32 s13, v250, 10
	v_and_b32_e32 v35, 15, v33
	v_lshlrev_b32_e32 v188, 13, v34
	s_mov_b32 s6, 0
	s_mov_b32 s14, 0x8000
	s_waitcnt vmcnt(11)
	ds_write_b128 v36, v[0:3]
	v_add_u32_e32 v0, 0x100, v33
	v_ashrrev_i32_e32 v1, 9, v0
	v_bfe_u32 v0, v0, 3, 6
	v_mul_i32_i24_e32 v133, 0x2400, v1
	v_mad_i32_i24 v1, v1, s4, 0
	v_mul_u32_u24_e32 v134, 0x90, v0
	v_add3_u32 v0, v1, v134, v130
	s_waitcnt vmcnt(10)
	ds_write_b128 v0, v[4:7]
	v_add_u32_e32 v0, 0x200, v33
	v_ashrrev_i32_e32 v0, 9, v0
	v_mul_i32_i24_e32 v135, 0x2400, v0
	v_mad_i32_i24 v0, v0, s4, 0
	v_add3_u32 v0, v0, v132, v130
	s_waitcnt vmcnt(9)
	ds_write_b128 v0, v[8:11]
	v_add_u32_e32 v0, 0x300, v33
	v_ashrrev_i32_e32 v1, 9, v0
	v_bfe_u32 v0, v0, 3, 6
	v_mul_i32_i24_e32 v136, 0x2400, v1
	v_mad_i32_i24 v1, v1, s4, 0
	v_mul_u32_u24_e32 v137, 0x90, v0
	v_add3_u32 v0, v1, v137, v130
	s_waitcnt vmcnt(8)
	ds_write_b128 v0, v[12:15]
	v_add_u32_e32 v0, 0x400, v33
	v_ashrrev_i32_e32 v0, 9, v0
	v_mul_i32_i24_e32 v138, 0x2400, v0
	v_mad_i32_i24 v0, v0, s4, 0
	v_add3_u32 v0, v0, v132, v130
	s_waitcnt vmcnt(7)
	ds_write_b128 v0, v[16:19]
	v_add_u32_e32 v0, 0x500, v33
	v_ashrrev_i32_e32 v1, 9, v0
	v_bfe_u32 v0, v0, 3, 6
	v_mul_i32_i24_e32 v139, 0x2400, v1
	v_mad_i32_i24 v1, v1, s4, 0
	v_mul_u32_u24_e32 v140, 0x90, v0
	v_add3_u32 v0, v1, v140, v130
	s_waitcnt vmcnt(6)
	ds_write_b128 v0, v[20:23]
	v_add_u32_e32 v0, 0x600, v33
	v_ashrrev_i32_e32 v0, 9, v0
	v_mul_i32_i24_e32 v141, 0x2400, v0
	v_mad_i32_i24 v0, v0, s4, 0
	v_add3_u32 v0, v0, v132, v130
	s_waitcnt vmcnt(5)
	ds_write_b128 v0, v[24:27]
	v_add_u32_e32 v0, 0x700, v33
	v_ashrrev_i32_e32 v1, 9, v0
	v_bfe_u32 v0, v0, 3, 6
	v_mul_i32_i24_e32 v142, 0x2400, v1
	v_mad_i32_i24 v1, v1, s4, 0
	v_mul_u32_u24_e32 v143, 0x90, v0
	v_readlane_b32 s4, v250, 13
	v_add3_u32 v0, v1, v143, v130
	v_readlane_b32 s5, v250, 14
	s_waitcnt vmcnt(4)
	ds_write_b128 v0, v[28:31]
	v_mul_u32_u24_e32 v33, 0x90, v35
	v_lshl_add_u64 v[0:1], s[4:5], 0, v[100:101]
	v_lshl_add_u64 v[4:5], s[4:5], 0, v[102:103]
	v_lshl_add_u64 v[8:9], s[4:5], 0, v[104:105]
	v_lshl_add_u64 v[12:13], s[4:5], 0, v[106:107]
	v_lshl_add_u64 v[16:17], s[4:5], 0, v[108:109]
	v_lshl_add_u64 v[20:21], s[4:5], 0, v[110:111]
	v_lshl_add_u64 v[24:25], s[4:5], 0, v[112:113]
	v_lshl_add_u64 v[28:29], s[4:5], 0, v[114:115]
	v_lshl_add_u64 v[36:37], s[4:5], 0, v[116:117]
	global_load_dwordx4 v[0:3], v[0:1], off
	v_readlane_b32 s4, v249, 3
	global_load_dwordx4 v[4:7], v[4:5], off
	v_readlane_b32 s5, v249, 4
	global_load_dwordx4 v[8:11], v[8:9], off
	s_nop 0
	global_load_dwordx4 v[12:15], v[12:13], off
	s_nop 0
	global_load_dwordx4 v[16:19], v[16:17], off
	s_nop 0
	global_load_dwordx4 v[20:23], v[20:21], off
	s_nop 0
	global_load_dwordx4 v[24:27], v[24:25], off
	s_nop 0
	global_load_dwordx4 v[28:31], v[28:29], off
	s_nop 0
	global_load_dwordx2 v[238:239], v[36:37], off
	global_load_dwordx2 v[240:241], v[36:37], off offset:32
	global_load_dwordx2 v[244:245], v[36:37], off offset:64
	global_load_dwordx2 v[254:255], v[36:37], off offset:96
	global_load_dwordx2 v[118:119], v189, s[12:13]
	v_lshlrev_b32_e32 v36, 4, v34
	v_add3_u32 v144, 0, v33, v36
	v_ashrrev_i32_e32 v33, 31, v32
	v_lshl_add_u64 v[32:33], v[32:33], 1, v[188:189]
	v_lshl_or_b32 v32, v35, 1, v32
	v_lshl_add_u64 v[120:121], s[4:5], 0, v[32:33]
	v_mov_b32_e32 v32, 0
	s_mov_b64 s[4:5], 0
	v_mov_b32_e32 v33, v32
	v_mov_b32_e32 v34, v32
	v_mov_b32_e32 v35, v32
	v_mov_b32_e32 v36, v32
	v_mov_b32_e32 v37, v32
	v_mov_b32_e32 v38, v32
	v_mov_b32_e32 v39, v32
	v_mov_b32_e32 v40, v32
	v_mov_b32_e32 v41, v32
	v_mov_b32_e32 v42, v32
	v_mov_b32_e32 v43, v32
	v_mov_b32_e32 v44, v32
	v_mov_b32_e32 v45, v32
	v_mov_b32_e32 v46, v32
	v_mov_b32_e32 v47, v32
	s_waitcnt vmcnt(0) lgkmcnt(0)
	v_mov_b32_e32 v243, v119
	s_barrier
; DI void gdn_scan_block(const Params& p, int bh, char* smem) {
;     ...
;     auto step = [&](const char* buf, int ck) {
;         const char* fb = buf + fr * 144 + fq * 16;
;         bf16x8 fa[4][2], fbq[4][2];
; #pragma unroll
;         for (int t = 0; t < 4; ++t) { fa[t][0] = *(const bf16x8*)(fb + t * 2304); fa[t][1] = *(const bf16x8*)(fb + t * 2304 + 64); }
; #pragma unroll
;         for (int t = 0; t < 4; ++t) { fbq[t][0] = *(const bf16x8*)(fb + 9216 + t * 2304); fbq[t][1] = *(const bf16x8*)(fb + 9216 + t * 2304 + 64); }
;         const bf16x8 Sb0 = pack2(S[0], S[1]), Sb1 = pack2(S[2], S[3]);
;         f32x4 vn[4];
; #pragma unroll
;         for (int ct = 0; ct < 4; ++ct) {
;             f32x4 acc = (f32x4){0.f, 0.f, 0.f, 0.f};
;             acc = mfma(fa[ct][0], Sb0, acc); acc = mfma(fa[ct][1], Sb1, acc);
;             f32x4 u; u[0] = __uint_as_float(uc[ct][0] << 16); u[1] = __uint_as_float(uc[ct][0] & 0xffff0000u);
;             u[2] = __uint_as_float(uc[ct][1] << 16); u[3] = __uint_as_float(uc[ct][1] & 0xffff0000u);
;             vn[ct] = u - acc;
;         }
; #pragma unroll
;         for (int t = 0; t < 4; ++t) { fa[t][0] = *(const bf16x8*)(fb + 18432 + t * 2304); fa[t][1] = *(const bf16x8*)(fb + 18432 + t * 2304 + 64); }
;         f32x4 o[4];
; #pragma unroll
;         for (int ct = 0; ct < 4; ++ct) {
;             f32x4 t = (f32x4){0.f, 0.f, 0.f, 0.f};
;             t = mfma(fbq[ct][0], Sb0, t); t = mfma(fbq[ct][1], Sb1, t);
;             o[ct] = t;
;         }
; #pragma unroll
;         for (int t = 0; t < 4; ++t) { fbq[t][0] = *(const bf16x8*)(fb + 27648 + t * 2304); fbq[t][1] = *(const bf16x8*)(fb + 27648 + t * 2304 + 64); }
;         const bf16x8 vb0 = pack2(vn[0], vn[1]), vb1 = pack2(vn[2], vn[3]);
;         bf16_t* op = p.hy + ((size_t)b * T_ + ck * 64 + fq * 4) * DM + h * 64 + e0 + fr;
; #pragma unroll
;         for (int ct = 0; ct < 4; ++ct) {
;             f32x4 t = o[ct];
;             t = mfma(fa[ct][0], vb0, t); t = mfma(fa[ct][1], vb1, t);
; #pragma unroll
;             for (int ii = 0; ii < 4; ++ii) op[(size_t)(ct * 16 + ii) * DM] = f2bf(t[ii]);
;         }
; #pragma unroll
;         for (int dt = 0; dt < 4; ++dt) {
;             f32x4 sacc = S[dt] * gl;
;             sacc = mfma(fbq[dt][0], vb0, sacc); sacc = mfma(fbq[dt][1], vb1, sacc);
;             S[dt] = sacc;
;         }
.LBB0_452:
	s_bitcmp1_b32 s6, 0
	s_cselect_b32 s7, 0x9000, 0
	v_add_u32_e32 v145, s7, v144
	ds_read_b128 v[56:59], v145
	ds_read_b128 v[60:63], v145 offset:64
	ds_read_b128 v[64:67], v145 offset:2304
	ds_read_b128 v[68:71], v145 offset:2368
	ds_read_b128 v[72:75], v145 offset:4608
	ds_read_b128 v[76:79], v145 offset:4672
	ds_read_b128 v[80:83], v145 offset:6912
	ds_read_b128 v[84:87], v145 offset:6976
	ds_read_b128 v[96:99], v145 offset:9216
	ds_read_b128 v[146:149], v145 offset:9280
	ds_read_b128 v[150:153], v145 offset:11520
	ds_read_b128 v[154:157], v145 offset:11584
	ds_read_b128 v[158:161], v145 offset:13824
	ds_read_b128 v[162:165], v145 offset:13888
	ds_read_b128 v[166:169], v145 offset:16128
	ds_read_b128 v[170:173], v145 offset:16192
	v_cvt_pk_bf16_f32 v174, v44, v45
	v_cvt_pk_bf16_f32 v175, v46, v47
	v_cvt_pk_bf16_f32 v176, v40, v41
	v_cvt_pk_bf16_f32 v177, v42, v43
	v_cvt_pk_bf16_f32 v178, v36, v37
	v_cvt_pk_bf16_f32 v179, v38, v39
	s_waitcnt lgkmcnt(14)
	v_mfma_f32_16x16x32_bf16 v[56:59], v[56:59], v[174:177], 0
	v_cvt_pk_bf16_f32 v180, v32, v33
	v_cvt_pk_bf16_f32 v181, v34, v35
	ds_read_b128 v[182:185], v145 offset:18432
	ds_read_b128 v[192:195], v145 offset:18496
	ds_read_b128 v[196:199], v145 offset:20736
	ds_read_b128 v[200:203], v145 offset:20800
	ds_read_b128 v[204:207], v145 offset:23040
	ds_read_b128 v[230:233], v145 offset:23104
	ds_read_b128 v[88:91], v145 offset:25344
	ds_read_b128 v[92:95], v145 offset:25408
	v_mfma_f32_16x16x32_bf16 v[56:59], v[60:63], v[178:181], v[56:59]
	v_lshlrev_b32_e32 v60, 16, v54
	v_and_b32_e32 v54, 0xffff0000, v54
	v_lshlrev_b32_e32 v61, 16, v55
	v_and_b32_e32 v55, 0xffff0000, v55
	v_lshlrev_b32_e32 v62, 16, v52
	s_nop 2
	v_sub_f32_e32 v59, v55, v59
	v_sub_f32_e32 v58, v61, v58
	v_sub_f32_e32 v61, v54, v57
	v_sub_f32_e32 v60, v60, v56
	s_waitcnt lgkmcnt(14)
	v_mfma_f32_16x16x32_bf16 v[54:57], v[64:67], v[174:177], 0
	v_and_b32_e32 v52, 0xffff0000, v52
	v_lshlrev_b32_e32 v63, 16, v53
	v_and_b32_e32 v53, 0xffff0000, v53
	v_mfma_f32_16x16x32_bf16 v[54:57], v[68:71], v[178:181], v[54:57]
	s_mov_b32 s7, 0x9000
	s_add_i32 s8, s6, 1
	s_bitcmp1_b32 s8, 0
	v_pk_mul_f32 v[34:35], v[34:35], v[118:119] op_sel_hi:[1,0]
	v_pk_mul_f32 v[32:33], v[32:33], v[118:119] op_sel_hi:[1,0]
	s_nop 1
	v_sub_f32_e32 v186, v53, v57
	v_sub_f32_e32 v187, v52, v55
	v_sub_f32_e32 v62, v62, v54
	v_mfma_f32_16x16x32_bf16 v[52:55], v[72:75], v[174:177], 0
	v_sub_f32_e32 v63, v63, v56
	v_lshlrev_b32_e32 v56, 16, v50
	v_and_b32_e32 v50, 0xffff0000, v50
	v_mfma_f32_16x16x32_bf16 v[52:55], v[76:79], v[178:181], v[52:55]
	v_lshlrev_b32_e32 v57, 16, v51
	v_and_b32_e32 v51, 0xffff0000, v51
	v_pk_mul_f32 v[46:47], v[46:47], v[118:119] op_sel_hi:[1,0]
	v_pk_mul_f32 v[44:45], v[44:45], v[118:119] op_sel_hi:[1,0]
	v_pk_mul_f32 v[42:43], v[42:43], v[118:119] op_sel_hi:[1,0]
	s_nop 2
	v_sub_f32_e32 v188, v51, v55
	v_sub_f32_e32 v208, v50, v53
	v_sub_f32_e32 v209, v56, v52
	v_mfma_f32_16x16x32_bf16 v[50:53], v[80:83], v[174:177], 0
	v_sub_f32_e32 v191, v57, v54
	v_lshlrev_b32_e32 v54, 16, v48
	v_and_b32_e32 v48, 0xffff0000, v48
	v_mfma_f32_16x16x32_bf16 v[50:53], v[84:87], v[178:181], v[50:53]
	v_lshlrev_b32_e32 v55, 16, v49
	v_and_b32_e32 v49, 0xffff0000, v49
	v_cvt_pk_bf16_f32 v56, v60, v61
	v_cvt_pk_bf16_f32 v57, v58, v59
	v_cvt_pk_bf16_f32 v58, v62, v187
	s_nop 2
	v_sub_f32_e32 v234, v49, v53
	v_sub_f32_e32 v236, v48, v51
	v_sub_f32_e32 v237, v54, v50
	v_mfma_f32_16x16x32_bf16 v[48:51], v[96:99], v[174:177], 0
	v_cvt_pk_bf16_f32 v59, v63, v186
	v_sub_f32_e32 v235, v55, v52
	v_cvt_pk_bf16_f32 v60, v209, v208
	v_mfma_f32_16x16x32_bf16 v[146:149], v[146:149], v[178:181], v[48:51]
	v_cvt_pk_bf16_f32 v61, v191, v188
	v_cvt_pk_bf16_f32 v62, v237, v236
	v_cvt_pk_bf16_f32 v63, v235, v234
	s_waitcnt lgkmcnt(13)
	v_mfma_f32_16x16x32_bf16 v[48:51], v[150:153], v[174:177], 0
	v_mul_f32_e64 v40, v40, v118
	v_mul_f32_e64 v41, v41, v118
	v_pk_mul_f32 v[38:39], v[38:39], v[118:119] op_sel_hi:[1,0]
	v_pk_mul_f32 v[36:37], v[36:37], v[118:119] op_sel_hi:[1,0]
	s_waitcnt lgkmcnt(12)
	v_mfma_f32_16x16x32_bf16 v[150:153], v[154:157], v[178:181], v[48:51]
	s_waitcnt lgkmcnt(11)
	v_mfma_f32_16x16x32_bf16 v[48:51], v[158:161], v[174:177], 0
	v_lshl_add_u64 v[158:159], v[120:121], 0, s[4:5]
	s_waitcnt lgkmcnt(7)
	v_mfma_f32_16x16x32_bf16 v[146:149], v[182:185], v[56:59], v[146:149]
	v_mfma_f32_16x16x32_bf16 v[154:157], v[162:165], v[178:181], v[48:51]
	v_mfma_f32_16x16x32_bf16 v[48:51], v[166:169], v[174:177], 0
	s_waitcnt lgkmcnt(6)
	v_mfma_f32_16x16x32_bf16 v[146:149], v[192:195], v[60:63], v[146:149]
	v_mfma_f32_16x16x32_bf16 v[96:99], v[170:173], v[178:181], v[48:51]
	ds_read_b128 v[80:83], v145 offset:27648
	ds_read_b128 v[84:87], v145 offset:27712
	ds_read_b128 v[72:75], v145 offset:29952
	ds_read_b128 v[76:79], v145 offset:30016
	ds_read_b128 v[64:67], v145 offset:32256
	ds_read_b128 v[68:71], v145 offset:32320
	ds_read_b128 v[48:51], v145 offset:34560
	ds_read_b128 v[52:55], v145 offset:34624
	v_bfe_u32 v145, v146, 16, 1
	v_add3_u32 v145, v146, v145, s2
	global_store_short_d16_hi v[158:159], v145, off
	v_bfe_u32 v145, v147, 16, 1
	v_add3_u32 v145, v147, v145, s2
	global_store_short_d16_hi v[158:159], v145, off offset:2048
	v_bfe_u32 v145, v148, 16, 1
	v_add_co_u32_e32 v146, vcc, s35, v158
	v_add3_u32 v145, v148, v145, s2
	s_nop 0
	v_addc_co_u32_e32 v147, vcc, 0, v159, vcc
	global_store_short_d16_hi v[146:147], v145, off
	v_bfe_u32 v145, v149, 16, 1
	v_add3_u32 v145, v149, v145, s2
	global_store_short_d16_hi v[146:147], v145, off offset:2048
	s_waitcnt lgkmcnt(13)
; DI bf16_t f2bf(float x) { unsigned u = __float_as_uint(x); u += 0x7fffu + ((u >> 16) & 1u); return (bf16_t)(u >> 16); }
; DI f32x4 mfma(bf16x8 a, bf16x8 b, f32x4 c) { return __builtin_amdgcn_mfma_f32_16x16x32_bf16(a, b, c, 0, 0, 0); }
; #define SC_LOAD(R, U, G, CK) do { const char* rn_ = recs + (size_t)(CK) * REC; \
;         _Pragma("unroll") for (int i_ = 0; i_ < 8; ++i_) R[i_] = *(const u32x4*)(rn_ + (tid + 256 * i_) * 16); \
;         _Pragma("unroll") for (int c_ = 0; c_ < 4; ++c_) U[c_] = *(const u32x2*)(rn_ + uoff + c_ * 32); G = glp[CK]; } while (0)
; #define SC_STORE(R, BUF) do { char* nb_ = smem + (BUF) * 36864; \
;         _Pragma("unroll") for (int i_ = 0; i_ < 8; ++i_) { const int cid_ = tid + 256 * i_, mat_ = cid_ >> 9, row_ = (cid_ >> 3) & 63, cc_ = cid_ & 7; \
;             *(u32x4*)(nb_ + mat_ * 9216 + row_ * 144 + cc_ * 16) = R[i_]; } } while (0)
; DI void gdn_scan_block(const Params& p, int bh, char* smem) {
;     ...
;         for (int ct = 0; ct < 4; ++ct) {
;             f32x4 t = o[ct];
;             t = mfma(fa[ct][0], vb0, t); t = mfma(fa[ct][1], vb1, t);
; #pragma unroll
;             for (int ii = 0; ii < 4; ++ii) op[(size_t)(ct * 16 + ii) * DM] = f2bf(t[ii]);
;         }
; #pragma unroll
;         for (int dt = 0; dt < 4; ++dt) {
;             f32x4 sacc = S[dt] * gl;
;             sacc = mfma(fbq[dt][0], vb0, sacc); sacc = mfma(fbq[dt][1], vb1, sacc);
;             S[dt] = sacc;
;         }
;     };
;     for (int ck = 0; ck < 256; ++ck) {
;         step(smem + (ck & 1) * 36864, ck);
;         SC_STORE(r1, (ck + 1) & 1);
; #pragma unroll
;         for (int c = 0; c < 4; ++c) uc[c] = u1[c];
;         gl = g1;
;         { const int cn = ck + 2 < 256 ? ck + 2 : 255; SC_LOAD(r1, u1, g1, cn); }
;         __syncthreads();
	v_mfma_f32_16x16x32_bf16 v[146:149], v[196:199], v[56:59], v[150:153]
	s_waitcnt lgkmcnt(12)
	v_mfma_f32_16x16x32_bf16 v[146:149], v[200:203], v[60:63], v[146:149]
	s_nop 0
	v_add_co_u32_e32 v150, vcc, s14, v158
	s_nop 1
	v_addc_co_u32_e32 v151, vcc, 0, v159, vcc
	v_add_co_u32_e32 v152, vcc, s7, v158
	s_nop 1
	v_bfe_u32 v145, v146, 16, 1
	v_add3_u32 v145, v146, v145, s2
	v_addc_co_u32_e32 v153, vcc, 0, v159, vcc
	s_waitcnt lgkmcnt(9)
	v_mfma_f32_16x16x32_bf16 v[88:91], v[88:91], v[56:59], v[96:99]
	global_store_short_d16_hi v[152:153], v145, off offset:-4096
	v_bfe_u32 v145, v147, 16, 1
	v_add3_u32 v145, v147, v145, s2
	global_store_short_d16_hi v[150:151], v145, off offset:2048
	v_bfe_u32 v145, v148, 16, 1
	v_add3_u32 v145, v148, v145, s2
	s_waitcnt lgkmcnt(8)
	v_mfma_f32_16x16x32_bf16 v[88:91], v[92:95], v[60:63], v[88:91]
	global_store_short_d16_hi v[152:153], v145, off
	v_bfe_u32 v145, v149, 16, 1
	v_add_co_u32_e32 v150, vcc, s33, v158
	v_add3_u32 v145, v149, v145, s2
	s_nop 0
	v_addc_co_u32_e32 v151, vcc, 0, v159, vcc
	s_mov_b32 s7, 0x11000
	global_store_short_d16_hi v[152:153], v145, off offset:2048
	v_add_co_u32_e32 v152, vcc, s7, v158
	v_bfe_u32 v92, v88, 16, 1
	s_nop 0
	v_addc_co_u32_e32 v153, vcc, 0, v159, vcc
	s_mov_b32 s7, 0x18000
	v_add3_u32 v88, v88, v92, s2
	v_add_co_u32_e32 v92, vcc, s7, v158
	s_mov_b32 s7, 0x19000
	s_nop 0
	v_addc_co_u32_e32 v93, vcc, 0, v159, vcc
	v_add_co_u32_e32 v94, vcc, s7, v158
	s_cselect_b32 s7, 0x9000, 0
	s_add_i32 s7, s7, 0
	v_mfma_f32_16x16x32_bf16 v[146:149], v[204:207], v[56:59], v[154:157]
	v_addc_co_u32_e32 v95, vcc, 0, v159, vcc
	global_store_short_d16_hi v[94:95], v88, off offset:-4096
	s_waitcnt lgkmcnt(1)
	v_mfma_f32_16x16x32_bf16 v[32:35], v[48:51], v[56:59], v[32:35]
	v_add_u32_e32 v48, s7, v131
	v_add3_u32 v48, v48, v132, v130
	s_waitcnt vmcnt(9)
	ds_write_b128 v48, v[0:3]
	v_add_u32_e32 v0, s7, v133
	v_add3_u32 v0, v0, v134, v130
	v_mfma_f32_16x16x32_bf16 v[146:149], v[230:233], v[60:63], v[146:149]
	ds_write_b128 v0, v[4:7]
	v_add_u32_e32 v0, s7, v135
	v_add3_u32 v0, v0, v132, v130
	ds_write_b128 v0, v[8:11]
	v_add_u32_e32 v0, s7, v136
	v_add3_u32 v0, v0, v137, v130
	s_nop 1
	v_bfe_u32 v145, v146, 16, 1
	ds_write_b128 v0, v[12:15]
	v_add_u32_e32 v0, s7, v138
	v_add3_u32 v145, v146, v145, s2
	v_add3_u32 v0, v0, v132, v130
	global_store_short_d16_hi v[152:153], v145, off offset:-4096
	v_bfe_u32 v145, v147, 16, 1
	v_bfe_u32 v88, v89, 16, 1
	ds_write_b128 v0, v[16:19]
	v_add_u32_e32 v0, s7, v139
	v_add3_u32 v145, v147, v145, s2
	v_add3_u32 v88, v89, v88, s2
	v_add3_u32 v0, v0, v140, v130
	s_min_u32 s9, s6, 0xfd
	global_store_short_d16_hi v[150:151], v145, off offset:2048
	v_bfe_u32 v145, v148, 16, 1
	global_store_short_d16_hi v[92:93], v88, off offset:2048
	v_bfe_u32 v88, v90, 16, 1
	ds_write_b128 v0, v[20:23]
	v_add_u32_e32 v0, s7, v141
	s_mul_i32 s6, s9, 0xa000
	v_add3_u32 v145, v148, v145, s2
	v_add3_u32 v88, v90, v88, s2
	v_mfma_f32_16x16x32_bf16 v[44:47], v[80:83], v[56:59], v[44:47]
	v_add3_u32 v0, v0, v132, v130
	s_add_i32 s6, s6, 0x14000
	global_store_short_d16_hi v[152:153], v145, off
	v_mfma_f32_16x16x32_bf16 v[40:43], v[72:75], v[56:59], v[40:43]
	v_bfe_u32 v145, v149, 16, 1
	global_store_short_d16_hi v[94:95], v88, off
	v_bfe_u32 v88, v91, 16, 1
	v_mfma_f32_16x16x32_bf16 v[36:39], v[64:67], v[56:59], v[36:39]
	ds_write_b128 v0, v[24:27]
	v_add_u32_e32 v0, s7, v142
	s_add_u32 s6, s10, s6
	v_add3_u32 v145, v149, v145, s2
	v_add3_u32 v88, v91, v88, s2
	v_add3_u32 v0, v0, v143, v130
	s_addc_u32 s7, s11, 0
	global_store_short_d16_hi v[152:153], v145, off offset:2048
	global_store_short_d16_hi v[94:95], v88, off offset:2048
	ds_write_b128 v0, v[28:31]
	v_lshl_add_u64 v[0:1], s[6:7], 0, v[100:101]
	v_lshl_add_u64 v[4:5], s[6:7], 0, v[102:103]
	v_lshl_add_u64 v[8:9], s[6:7], 0, v[104:105]
	v_lshl_add_u64 v[12:13], s[6:7], 0, v[106:107]
	v_lshl_add_u64 v[16:17], s[6:7], 0, v[108:109]
	v_lshl_add_u64 v[20:21], s[6:7], 0, v[110:111]
	v_lshl_add_u64 v[24:25], s[6:7], 0, v[112:113]
	v_lshl_add_u64 v[28:29], s[6:7], 0, v[114:115]
	v_lshl_add_u64 v[122:123], s[6:7], 0, v[116:117]
	s_lshl_b32 s6, s9, 2
	v_mfma_f32_16x16x32_bf16 v[44:47], v[84:87], v[60:63], v[44:47]
	global_load_dwordx4 v[0:3], v[0:1], off
	s_add_u32 s4, s4, 0x20000
	global_load_dwordx4 v[4:7], v[4:5], off
	v_mfma_f32_16x16x32_bf16 v[40:43], v[76:79], v[60:63], v[40:43]
	global_load_dwordx4 v[8:11], v[8:9], off
	s_addc_u32 s5, s5, 0
	global_load_dwordx4 v[12:15], v[12:13], off
	v_mfma_f32_16x16x32_bf16 v[36:39], v[68:71], v[60:63], v[36:39]
	global_load_dwordx4 v[16:19], v[16:17], off
	s_cmp_lg_u32 s4, 0x2000000
	global_load_dwordx4 v[20:23], v[20:21], off
	s_waitcnt lgkmcnt(8)
	v_mfma_f32_16x16x32_bf16 v[32:35], v[52:55], v[60:63], v[32:35]
	global_load_dwordx4 v[24:27], v[24:25], off
	global_load_dwordx4 v[28:31], v[28:29], off
	s_nop 0
	v_mov_b64_e32 v[50:51], v[244:245]
	v_mov_b64_e32 v[48:49], v[254:255]
	v_mov_b32_e32 v118, v243
	v_mov_b32_e32 v124, s6
	s_nop 1
	v_mov_b64_e32 v[52:53], v[240:241]
	v_mov_b64_e32 v[54:55], v[238:239]
	global_load_dwordx2 v[238:239], v[122:123], off
	global_load_dwordx2 v[240:241], v[122:123], off offset:32
	global_load_dwordx2 v[244:245], v[122:123], off offset:64
	global_load_dwordx2 v[254:255], v[122:123], off offset:96
	global_load_dword v243, v124, s[12:13] offset:8
	s_mov_b32 s6, s8
	s_waitcnt lgkmcnt(0)
	s_barrier
	s_cbranch_scc1 .LBB0_452
	s_waitcnt vmcnt(0)
	s_setprio 0
